# v33 = v29 + post-step-0 barrier waits vmcnt(3) only (the K1 fragment prefetch stays in flight across it)
# speedup vs baseline: 1.0008x; 1.0001x over previous
.LBB0_569:
	s_or_b64 exec, exec, s[48:49]
	s_add_i32 s48, s81, 0x100
	s_lshr_b32 s80, s48, 6
	s_add_u32 s66, s8, 0x18000
	s_addc_u32 s67, s9, 0
	s_cmp_lg_u32 0, -1
	s_cselect_b32 s48, 0, 0
	s_add_i32 s48, s48, s73
	s_add_i32 s48, s48, 0xe000
	s_mov_b32 m0, s48
	s_nop 0
	global_load_lds_dwordx4 v185, s[66:67]
	ds_read_b128 v[80:83], v179 offset:12288
	ds_read_b128 v[136:139], v179 offset:12800
	ds_read_b128 v[140:143], v179 offset:14336
	v_exp_f32_e32 v48, v16
	v_exp_f32_e32 v49, v17
	v_exp_f32_e32 v50, v18
	v_exp_f32_e32 v51, v19
	v_exp_f32_e32 v52, v20
	v_exp_f32_e32 v53, v21
	v_exp_f32_e32 v54, v22
	v_exp_f32_e32 v55, v23
	v_exp_f32_e32 v56, v24
	v_exp_f32_e32 v57, v25
	v_exp_f32_e32 v58, v26
	v_exp_f32_e32 v59, v27
	v_exp_f32_e32 v60, v28
	v_exp_f32_e32 v61, v29
	v_exp_f32_e32 v62, v30
	v_exp_f32_e32 v63, v31
	v_exp_f32_e32 v32, v0
	v_exp_f32_e32 v33, v1
	v_exp_f32_e32 v34, v2
	v_exp_f32_e32 v35, v3
	v_exp_f32_e32 v36, v4
	v_exp_f32_e32 v37, v5
	v_exp_f32_e32 v38, v6
	v_exp_f32_e32 v39, v7
	v_exp_f32_e32 v40, v8
	v_exp_f32_e32 v41, v9
	v_exp_f32_e32 v42, v10
	v_exp_f32_e32 v43, v11
	v_exp_f32_e32 v44, v12
	v_exp_f32_e32 v45, v13
	v_exp_f32_e32 v46, v14
	v_exp_f32_e32 v47, v15
	s_waitcnt vmcnt(3)
	s_barrier
	s_mov_b32 s86, 0
	s_andn2_b64 vcc, exec, s[0:1]
	s_mov_b32 s0, 1
	s_cbranch_vccnz .LBB0_595
	s_add_u32 s68, s8, 0x48000
	s_addc_u32 s69, s9, 0
	s_add_u32 s48, s64, 0xb4000
	s_addc_u32 s49, s65, 0
	v_mov_b32_e32 v16, v153
	v_mov_b32_e32 v17, v153
	s_add_u32 s8, s46, 0x5000
	v_mov_b32_e32 v18, v153
	v_mov_b32_e32 v19, v153
	v_mov_b32_e32 v20, v153
	v_mov_b32_e32 v21, v153
	v_mov_b32_e32 v22, v153
	v_mov_b32_e32 v23, v153
	v_mov_b32_e32 v24, v153
	v_mov_b32_e32 v25, v153
	v_mov_b32_e32 v26, v153
	v_mov_b32_e32 v27, v153
	v_mov_b32_e32 v28, v153
	v_mov_b32_e32 v29, v153
	v_mov_b32_e32 v30, v153
	v_mov_b32_e32 v31, v153
	v_mov_b64_e32 v[0:1], v[16:17]
	s_addc_u32 s9, s47, 0
	s_mov_b32 s0, 0
	s_movk_i32 s83, 0x6000
	s_movk_i32 s82, 0x3000
	s_movk_i32 s86, 0x4000
	s_movk_i32 s79, 0x2000
	s_mov_b64 s[60:61], 0
	v_mov_b32_e32 v166, 0
	s_mov_b32 s87, 6
	v_mov_b64_e32 v[2:3], v[18:19]
	v_mov_b64_e32 v[4:5], v[20:21]
	v_mov_b64_e32 v[6:7], v[22:23]
	v_mov_b64_e32 v[8:9], v[24:25]
	v_mov_b64_e32 v[10:11], v[26:27]
	v_mov_b64_e32 v[12:13], v[28:29]
	v_mov_b64_e32 v[14:15], v[30:31]
	s_mov_b32 s84, 0
